# remaining 20 percent of layer 1-3 weight transposes now done by attention workgroups after their phase-4 queues drain; phase 0 converts only layer 0 and the memory KV weights
# speedup vs baseline: 1.0030x; 1.0024x over previous
; #define NEXT_ITEM(CI, LIMIT)                                   \
;     __syncthreads();                                           \
;     if (ltid() == 0) s_item = atomicAdd(cnt + (CI), 1);   \
;     __syncthreads();                                           \
;     const int it = s_item;                                     \
;     if (it >= (LIMIT)) break;
; __device__ __forceinline__ void phase_w(const Params p, char* smem) {
;     ...
;   for (int t = lbid(); t < L_ * PER_L; t += gridDim.x) {
;     int l = t / PER_L, r = t % PER_L;
; template <int ATM>
; __device__ __forceinline__ void phase_attn_scan(const Params p, int l, char* smem) {
;     ...
;   if (ATM & 4) while (true) {
;     NEXT_ITEM(2, 4 * QB2)
;     int h = it / QB2, qb = it % QB2;
;     attn_item<128, ATT_NSUB>(P + O_MQ + h * 128, NINP, (const u16*)(ws + OFF_KMEM) + (size_t)(l * 4 + h) * 256 * 128, 128,
;                              (const u16*)(ws + OFF_VTMEM) + (size_t)(l * 4 + h) * 128 * 256, 256, 256,
;                              OB + (size_t)(12 + h) * S_ * 128, qb, false, nullptr, 0, pos, kpmm, smem, pos, nullptr);
;   }
.Lattn_exit:
	s_cmp_lt_u32 s73, 64
	s_cbranch_scc1 .LBB0_248
	v_readlane_b32 s0, v244, 43
	s_cmp_gt_u32 s0, 2
	s_cbranch_scc1 .LBB0_248
	s_sub_i32 s20, s73, 64
	s_cmp_lt_u32 s73, 256
	s_cbranch_scc1 .Lattn_w
	s_sub_i32 s20, s73, 128
.Lattn_w:
	s_add_i32 s0, s0, 1
	s_mul_i32 s1, s0, 0x2768
	s_add_i32 s101, s1, 9575
	s_add_i32 s20, s20, s1
	s_add_i32 s20, s20, 7680
	s_movk_i32 s100, 0x180
	s_waitcnt lgkmcnt(0)
	s_barrier
	s_branch .Ltramp_554

; __device__ __forceinline__ void phase_w(const Params p, char* smem) {
;     ...
;   for (int t = lbid(); t < L_ * PER_L; t += gridDim.x) {
;     int l = t / PER_L, r = t % PER_L;
.Lw_exit:
	s_cmp_lg_u32 s100, 0x200
	s_cbranch_scc1 .Lw_ret4
	s_cmp_eq_u32 s101, 0x9d9f
	s_cbranch_scc1 .LBB0_575
	s_add_i32 s20, s101, 9577
	s_add_i32 s101, s101, 0x2768
	s_add_i32 s20, s20, s73
	s_branch .LBB0_554
